# filter dealing plus wave-uniform fast paths in the hyena_post context convolution
# speedup vs baseline: 1.0082x; 1.0013x over previous
; __device__ __forceinline__ void ph_filter(const Params& P, char* smem) {
;     ...
;   constexpr int NTT = (SEQ + CTX_LEN) / 64, NCT = HY_CH / 64;
;   const float max_decay = logf(1e-2f) / 0.3f, min_decay = logf(1e-2f) / 1.5f;
;   for (int u = blockIdx.x; u < NTT * NCT; u += gridDim.x) {
;     const int tt = u % NTT, ct = u / NTT;
;     const int gp0 = tt * 64, c0 = ct * 64;
;     const bool isc = gp0 >= SEQ;
;     const int L = isc ? CTX_LEN : SEQ;
;     const int t0 = isc ? gp0 - SEQ : gp0;
;     __syncthreads();
.Lflt_e:
	s_cmp_lt_u32 s54, 88
	s_cbranch_scc0 .Lflt_e17
	s_mul_i32 s50, s54, 18
	s_add_u32 s50, s50, 672
	s_add_u32 s52, s50, 18
	s_branch .Lflt_go
.Lflt_e17:
	s_sub_u32 s54, s54, 88
	s_mul_i32 s50, s54, 17
	s_add_u32 s50, s50, 2256
	s_add_u32 s52, s50, 17
